# SSD scan: all 15 state loads + 15 decay loads issued before one wait (was load, wait vmcnt(0), exp per chunk)
# baseline (speedup 1.0000x reference)
; DI void ssd_scan(float* STATES, const float* TOT, int gtid, int gthreads) {
;     for (int it = gtid; it < 8 * 4 * 2 * 64 * 32; it += gthreads) {
;         const int n4 = it & 31, p = (it >> 5) & 63, dir = (it >> 11) & 1, h = (it >> 12) & 3, b = it >> 14;
;         f32x4 v[16]; float e[16];
; #pragma unroll
;         for (int st = 0; st < 16; ++st) { const int c = dir ? 15 - st : st; const int hd = ((b * 16 + c) * 4 + h) * 2 + dir;
;             v[st] = *(const f32x4*)(STATES + ((size_t)hd * 64 + p) * 128 + n4 * 4); e[st] = __expf(TOT[hd]); }
.LBB0_418:
	v_and_b32_e32 v6, 0x1f80, v5
	v_lshlrev_b32_e32 v188, 2, v6
	v_and_b32_e32 v10, 0x7c, v5
	v_lshrrev_b32_e32 v8, 11, v4
	v_lshl_add_u64 v[6:7], s[12:13], 0, v[188:189]
	v_lshlrev_b32_e32 v188, 2, v10
	v_bfe_i32 v9, v4, 11, 1
	v_lshl_add_u64 v[66:67], v[6:7], 0, v[188:189]
	v_ashrrev_i32_e32 v7, 7, v4
	v_and_b32_e32 v8, 6, v8
	s_movk_i32 s2, 0xff80
	v_bfe_u32 v73, v4, 11, 1
	v_and_b32_e32 v6, 0x78, v9
	v_and_or_b32 v77, v7, s2, v8
	v_or3_b32 v10, v73, v6, v77
	v_ashrrev_i32_e32 v11, 31, v10
	v_lshlrev_b64 v[6:7], 15, v[10:11]
	v_lshl_add_u64 v[68:69], v[66:67], 0, v[6:7]
	v_lshl_add_u64 v[10:11], v[10:11], 2, s[70:71]
	global_load_dwordx4 v[6:9], v[68:69], off
	v_cmp_eq_u32_e32 vcc, 0, v73
	global_load_dword v81, v[10:11], off
	v_lshlrev_b32_e32 v40, 3, v73
	v_add_u32_e32 v4, s56, v4
	s_mov_b32 s2, 0x1ffff
	v_add_u32_e32 v5, s75, v5
	v_cndmask_b32_e64 v10, v235, 8, vcc
	v_or3_b32 v14, v73, v10, v77
	v_ashrrev_i32_e32 v15, 31, v14
	v_lshlrev_b64 v[10:11], 15, v[14:15]
	v_lshl_add_u64 v[70:71], v[66:67], 0, v[10:11]
	v_lshl_add_u64 v[14:15], v[14:15], 2, s[70:71]
	global_load_dwordx4 v[10:13], v[70:71], off
	s_nop 0
	global_load_dword v72, v[14:15], off
	v_cndmask_b32_e64 v14, v236, 16, vcc
	v_or3_b32 v18, v73, v14, v77
	v_ashrrev_i32_e32 v19, 31, v18
	v_lshlrev_b64 v[14:15], 15, v[18:19]
	v_lshl_add_u64 v[74:75], v[66:67], 0, v[14:15]
	v_lshl_add_u64 v[18:19], v[18:19], 2, s[70:71]
	global_load_dwordx4 v[14:17], v[74:75], off
	s_nop 0
	global_load_dword v76, v[18:19], off
	v_cndmask_b32_e64 v18, v237, 24, vcc
	v_or3_b32 v22, v73, v18, v77
	v_ashrrev_i32_e32 v23, 31, v22
	v_lshlrev_b64 v[18:19], 15, v[22:23]
	v_lshl_add_u64 v[78:79], v[66:67], 0, v[18:19]
	v_lshl_add_u64 v[22:23], v[22:23], 2, s[70:71]
	global_load_dwordx4 v[18:21], v[78:79], off
	s_nop 0
	global_load_dword v80, v[22:23], off
	v_cndmask_b32_e64 v22, v238, 32, vcc
	v_or3_b32 v26, v73, v22, v77
	v_ashrrev_i32_e32 v27, 31, v26
	v_lshlrev_b64 v[22:23], 15, v[26:27]
	v_lshl_add_u64 v[82:83], v[66:67], 0, v[22:23]
	v_lshl_add_u64 v[26:27], v[26:27], 2, s[70:71]
	global_load_dwordx4 v[22:25], v[82:83], off
	s_nop 0
	global_load_dword v84, v[26:27], off
	v_cndmask_b32_e64 v26, v239, 40, vcc
	v_or3_b32 v30, v73, v26, v77
	v_ashrrev_i32_e32 v31, 31, v30
	v_lshlrev_b64 v[26:27], 15, v[30:31]
	v_lshl_add_u64 v[86:87], v[66:67], 0, v[26:27]
	v_lshl_add_u64 v[30:31], v[30:31], 2, s[70:71]
	global_load_dwordx4 v[26:29], v[86:87], off
	s_nop 0
	global_load_dword v88, v[30:31], off
	v_cndmask_b32_e64 v30, v240, 48, vcc
	v_or3_b32 v34, v73, v30, v77
	v_ashrrev_i32_e32 v35, 31, v34
	v_lshlrev_b64 v[30:31], 15, v[34:35]
	v_lshl_add_u64 v[90:91], v[66:67], 0, v[30:31]
	v_lshl_add_u64 v[34:35], v[34:35], 2, s[70:71]
	global_load_dwordx4 v[30:33], v[90:91], off
	s_nop 0
	global_load_dword v92, v[34:35], off
	v_or3_b32 v34, v40, v77, v73
	v_add_u32_e32 v38, 56, v34
	v_ashrrev_i32_e32 v39, 31, v38
	v_lshlrev_b64 v[34:35], 15, v[38:39]
	v_lshl_add_u64 v[94:95], v[66:67], 0, v[34:35]
	v_lshl_add_u64 v[38:39], v[38:39], 2, s[70:71]
	global_load_dwordx4 v[34:37], v[94:95], off
	s_nop 0
	global_load_dword v96, v[38:39], off
	v_or_b32_e32 v38, 64, v73
	v_sub_u32_e32 v38, v38, v40
	v_or_b32_e32 v42, v38, v77
	v_ashrrev_i32_e32 v43, 31, v42
	v_lshlrev_b64 v[38:39], 15, v[42:43]
	v_lshl_add_u64 v[98:99], v[66:67], 0, v[38:39]
	v_lshl_add_u64 v[42:43], v[42:43], 2, s[70:71]
	global_load_dwordx4 v[38:41], v[98:99], off
	s_nop 0
	global_load_dword v100, v[42:43], off
	v_cndmask_b32_e32 v42, 48, v240, vcc
	v_or3_b32 v46, v73, v42, v77
	v_ashrrev_i32_e32 v47, 31, v46
	v_lshlrev_b64 v[42:43], 15, v[46:47]
	v_lshl_add_u64 v[102:103], v[66:67], 0, v[42:43]
	v_lshl_add_u64 v[46:47], v[46:47], 2, s[70:71]
	global_load_dwordx4 v[42:45], v[102:103], off
	s_nop 0
	global_load_dword v104, v[46:47], off
	v_cndmask_b32_e32 v46, 40, v239, vcc
	v_or3_b32 v50, v73, v46, v77
	v_ashrrev_i32_e32 v51, 31, v50
	v_lshlrev_b64 v[46:47], 15, v[50:51]
	v_lshl_add_u64 v[106:107], v[66:67], 0, v[46:47]
	v_lshl_add_u64 v[50:51], v[50:51], 2, s[70:71]
	global_load_dwordx4 v[46:49], v[106:107], off
	s_nop 0
	global_load_dword v108, v[50:51], off
	v_cndmask_b32_e32 v50, 32, v238, vcc
	v_or3_b32 v54, v73, v50, v77
	v_ashrrev_i32_e32 v55, 31, v54
	v_lshlrev_b64 v[50:51], 15, v[54:55]
	v_lshl_add_u64 v[110:111], v[66:67], 0, v[50:51]
	v_lshl_add_u64 v[54:55], v[54:55], 2, s[70:71]
	global_load_dwordx4 v[50:53], v[110:111], off
	s_nop 0
	global_load_dword v112, v[54:55], off
	v_cndmask_b32_e32 v54, 24, v237, vcc
	v_or3_b32 v58, v73, v54, v77
	v_ashrrev_i32_e32 v59, 31, v58
	v_lshlrev_b64 v[54:55], 15, v[58:59]
	v_lshl_add_u64 v[114:115], v[66:67], 0, v[54:55]
	v_lshl_add_u64 v[58:59], v[58:59], 2, s[70:71]
	global_load_dwordx4 v[54:57], v[114:115], off
	s_nop 0
	global_load_dword v116, v[58:59], off
	v_cndmask_b32_e32 v58, 16, v236, vcc
	v_or3_b32 v62, v73, v58, v77
	v_ashrrev_i32_e32 v63, 31, v62
	v_lshlrev_b64 v[58:59], 15, v[62:63]
	v_lshl_add_u64 v[118:119], v[66:67], 0, v[58:59]
	v_lshl_add_u64 v[62:63], v[62:63], 2, s[70:71]
	global_load_dwordx4 v[58:61], v[118:119], off
	s_nop 0
	global_load_dword v120, v[62:63], off
	v_cndmask_b32_e32 v62, 8, v235, vcc
	v_or3_b32 v122, v73, v62, v77
	v_ashrrev_i32_e32 v123, 31, v122
	v_lshlrev_b64 v[62:63], 15, v[122:123]
	v_lshl_add_u64 v[124:125], v[66:67], 0, v[62:63]
	v_lshl_add_u64 v[122:123], v[122:123], 2, s[70:71]
	global_load_dwordx4 v[62:65], v[124:125], off
	global_load_dword v85, v[122:123], off
	s_waitcnt vmcnt(0)
; DI void ssd_scan(float* STATES, const float* TOT, int gtid, int gthreads) {
;     ...
;         for (int st = 0; st < 16; ++st) { const int c = dir ? 15 - st : st; const int hd = ((b * 16 + c) * 4 + h) * 2 + dir;
;             v[st] = *(const f32x4*)(STATES + ((size_t)hd * 64 + p) * 128 + n4 * 4); e[st] = __expf(TOT[hd]); }
;         f32x4 carry = (f32x4){0.f, 0.f, 0.f, 0.f};
; #pragma unroll
;         for (int st = 0; st < 16; ++st) { const int c = dir ? 15 - st : st; const int hd = ((b * 16 + c) * 4 + h) * 2 + dir;
;             *(f32x4*)(STATES + ((size_t)hd * 64 + p) * 128 + n4 * 4) = carry; carry = carry * e[st] + v[st]; }
	v_mul_f32_e32 v81, 0x3fb8aa3b, v81
	v_exp_f32_e32 v81, v81
	v_mul_f32_e32 v72, 0x3fb8aa3b, v72
	v_exp_f32_e32 v72, v72
	v_mul_f32_e32 v76, 0x3fb8aa3b, v76
	v_exp_f32_e32 v76, v76
	v_mul_f32_e32 v80, 0x3fb8aa3b, v80
	v_exp_f32_e32 v80, v80
	v_mul_f32_e32 v84, 0x3fb8aa3b, v84
	v_exp_f32_e32 v84, v84
	v_mul_f32_e32 v88, 0x3fb8aa3b, v88
	v_exp_f32_e32 v88, v88
	v_mul_f32_e32 v92, 0x3fb8aa3b, v92
	v_exp_f32_e32 v92, v92
	v_mul_f32_e32 v96, 0x3fb8aa3b, v96
	v_exp_f32_e32 v96, v96
	v_mul_f32_e32 v100, 0x3fb8aa3b, v100
	v_exp_f32_e32 v100, v100
	v_mul_f32_e32 v104, 0x3fb8aa3b, v104
	v_exp_f32_e32 v104, v104
	v_mul_f32_e32 v108, 0x3fb8aa3b, v108
	v_exp_f32_e32 v108, v108
	v_mul_f32_e32 v112, 0x3fb8aa3b, v112
	v_exp_f32_e32 v112, v112
	v_mul_f32_e32 v116, 0x3fb8aa3b, v116
	v_exp_f32_e32 v116, v116
	v_mul_f32_e32 v120, 0x3fb8aa3b, v120
	v_exp_f32_e32 v120, v120
	v_mul_f32_e32 v85, 0x3fb8aa3b, v85
	global_store_dwordx4 v[68:69], v[0:3], off
	v_mul_f32_e32 v68, 0, v81
	v_pk_add_f32 v[8:9], v[8:9], v[68:69] op_sel_hi:[1,0]
	v_pk_add_f32 v[6:7], v[6:7], v[68:69] op_sel_hi:[1,0]
	global_store_dwordx4 v[70:71], v[6:9], off
	v_exp_f32_e32 v122, v85
	v_cndmask_b32_e32 v85, 0, v241, vcc
	v_pk_fma_f32 v[8:9], v[8:9], v[72:73], v[12:13] op_sel_hi:[1,0,1]
	v_pk_fma_f32 v[6:7], v[6:7], v[72:73], v[10:11] op_sel_hi:[1,0,1]
	global_store_dwordx4 v[74:75], v[6:9], off
	v_or3_b32 v126, v73, v85, v77
	v_ashrrev_i32_e32 v127, 31, v126
	v_pk_fma_f32 v[8:9], v[8:9], v[76:77], v[16:17] op_sel_hi:[1,0,1]
	v_pk_fma_f32 v[6:7], v[6:7], v[76:77], v[14:15] op_sel_hi:[1,0,1]
	global_store_dwordx4 v[78:79], v[6:9], off
	v_lshlrev_b64 v[10:11], 15, v[126:127]
	v_cmp_lt_i32_e32 vcc, s2, v4
	v_pk_fma_f32 v[8:9], v[8:9], v[80:81], v[20:21] op_sel_hi:[1,0,1]
	v_pk_fma_f32 v[6:7], v[6:7], v[80:81], v[18:19] op_sel_hi:[1,0,1]
	global_store_dwordx4 v[82:83], v[6:9], off
	v_lshl_add_u64 v[10:11], v[66:67], 0, v[10:11]
	s_or_b64 s[20:21], vcc, s[20:21]
	v_pk_fma_f32 v[8:9], v[8:9], v[84:85], v[24:25] op_sel_hi:[1,0,1]
	v_pk_fma_f32 v[6:7], v[6:7], v[84:85], v[22:23] op_sel_hi:[1,0,1]
	global_store_dwordx4 v[86:87], v[6:9], off
	s_nop 1
	v_pk_fma_f32 v[8:9], v[8:9], v[88:89], v[28:29] op_sel_hi:[1,0,1]
	v_pk_fma_f32 v[6:7], v[6:7], v[88:89], v[26:27] op_sel_hi:[1,0,1]
	global_store_dwordx4 v[90:91], v[6:9], off
	s_nop 1
	v_pk_fma_f32 v[8:9], v[8:9], v[92:93], v[32:33] op_sel_hi:[1,0,1]
	v_pk_fma_f32 v[6:7], v[6:7], v[92:93], v[30:31] op_sel_hi:[1,0,1]
	global_store_dwordx4 v[94:95], v[6:9], off
	s_nop 1
	v_pk_fma_f32 v[8:9], v[8:9], v[96:97], v[36:37] op_sel_hi:[1,0,1]
	v_pk_fma_f32 v[6:7], v[6:7], v[96:97], v[34:35] op_sel_hi:[1,0,1]
	global_store_dwordx4 v[98:99], v[6:9], off
	s_nop 1
	v_pk_fma_f32 v[8:9], v[8:9], v[100:101], v[40:41] op_sel_hi:[1,0,1]
	v_pk_fma_f32 v[6:7], v[6:7], v[100:101], v[38:39] op_sel_hi:[1,0,1]
	global_store_dwordx4 v[102:103], v[6:9], off
	s_nop 1
	v_pk_fma_f32 v[8:9], v[8:9], v[104:105], v[44:45] op_sel_hi:[1,0,1]
	v_pk_fma_f32 v[6:7], v[6:7], v[104:105], v[42:43] op_sel_hi:[1,0,1]
	global_store_dwordx4 v[106:107], v[6:9], off
	s_nop 1
	v_pk_fma_f32 v[8:9], v[8:9], v[108:109], v[48:49] op_sel_hi:[1,0,1]
	v_pk_fma_f32 v[6:7], v[6:7], v[108:109], v[46:47] op_sel_hi:[1,0,1]
	global_store_dwordx4 v[110:111], v[6:9], off
	s_nop 1
	v_pk_fma_f32 v[8:9], v[8:9], v[112:113], v[52:53] op_sel_hi:[1,0,1]
	v_pk_fma_f32 v[6:7], v[6:7], v[112:113], v[50:51] op_sel_hi:[1,0,1]
	global_store_dwordx4 v[114:115], v[6:9], off
	s_nop 1
	v_pk_fma_f32 v[8:9], v[8:9], v[116:117], v[56:57] op_sel_hi:[1,0,1]
	v_pk_fma_f32 v[6:7], v[6:7], v[116:117], v[54:55] op_sel_hi:[1,0,1]
	global_store_dwordx4 v[118:119], v[6:9], off
	s_nop 1
	v_pk_fma_f32 v[8:9], v[8:9], v[120:121], v[60:61] op_sel_hi:[1,0,1]
	v_pk_fma_f32 v[6:7], v[6:7], v[120:121], v[58:59] op_sel_hi:[1,0,1]
	global_store_dwordx4 v[124:125], v[6:9], off
	s_nop 1
	v_pk_fma_f32 v[8:9], v[8:9], v[122:123], v[64:65] op_sel_hi:[1,0,1]
	v_pk_fma_f32 v[6:7], v[6:7], v[122:123], v[62:63] op_sel_hi:[1,0,1]
	global_store_dwordx4 v[10:11], v[6:9], off
	s_andn2_b64 exec, exec, s[20:21]
	s_cbranch_execnz .LBB0_418
